# r16 + counted wait in the MLA unit prologue: vmcnt(3) keeps the second tile's three loads in flight across the first tile's LDS writes
# baseline (speedup 1.0000x reference)
.LBB0_262:
	s_lshl_b32 s9, s2, 8
	s_add_i32 s10, s52, s9
	s_ashr_i32 s11, s10, 31
	s_mul_i32 s28, s10, 0x600
	s_mul_hi_i32 s2, s10, 0x600
	s_add_u32 s30, s18, s28
	s_addc_u32 s31, s19, s2
	s_mul_i32 s2, s8, 0x60
	s_lshl_b64 s[28:29], s[2:3], 1
	v_add_lshl_u32 v0, s9, v192, 4
	s_add_u32 s28, s30, s28
	v_ashrrev_i32_e32 v1, 31, v0
	s_addc_u32 s29, s31, s29
	s_ashr_i32 s53, s52, 31
	v_lshlrev_b64 v[0:1], 2, v[0:1]
	s_lshl_b64 s[72:73], s[52:53], 11
	v_lshl_add_u64 v[8:9], v[162:163], 0, v[0:1]
	v_lshl_add_u64 v[4:5], v[164:165], 0, v[0:1]
	s_add_u32 s2, s20, s72
	global_load_dwordx4 v[0:3], v[4:5], off offset:16
	global_load_dwordx4 v[16:19], v[4:5], off
	s_nop 0
	global_load_dwordx4 v[4:7], v[8:9], off offset:16
	global_load_dwordx4 v[20:23], v[8:9], off
	v_lshl_add_u64 v[8:9], s[28:29], 0, v[148:149]
	s_addc_u32 s9, s21, s73
	s_lshl_b32 s28, s8, 8
	s_add_u32 s76, s2, s28
	s_addc_u32 s77, s9, 0
	s_lshl_b64 s[74:75], s[52:53], 6
	s_add_u32 s52, s22, s74
	s_addc_u32 s53, s23, s75
	v_mov_b32_e32 v181, v151
	v_mov_b32_e32 v179, v151
	v_lshl_add_u64 v[24:25], s[76:77], 0, v[154:155]
	v_lshlrev_b32_e32 v150, 1, v152
	v_lshl_add_u64 v[32:33], s[52:53], 0, v[180:181]
	v_mov_b32_e32 v183, v151
	v_lshl_add_u64 v[36:37], v[8:9], 0, v[178:179]
	v_lshl_add_u64 v[28:29], v[24:25], 0, v[150:151]
	s_waitcnt lgkmcnt(0)
	v_lshl_add_u64 v[44:45], v[32:33], 0, v[182:183]
	global_load_dwordx4 v[8:11], v[36:37], off offset:128
	global_load_dwordx4 v[12:15], v[36:37], off offset:160
	global_load_dwordx4 v[116:119], v[36:37], off
	global_load_dwordx4 v[112:115], v[36:37], off offset:32
	global_load_dwordx4 v[24:27], v[28:29], off offset:128
	s_nop 0
	global_load_dwordx4 v[28:31], v[28:29], off
	s_nop 0
	global_load_dwordx4 v[32:35], v[44:45], off
	global_load_dwordx4 v[124:127], v[36:37], off offset:64
	global_load_dwordx4 v[120:123], v[36:37], off offset:96
	v_lshl_add_u64 v[36:37], s[76:77], 0, v[156:157]
	v_lshl_add_u64 v[40:41], v[36:37], 0, v[150:151]
	global_load_dwordx4 v[36:39], v[40:41], off offset:128
	s_nop 0
	global_load_dwordx4 v[40:43], v[40:41], off
	v_add_co_u32_e32 v48, vcc, s24, v44
	v_add_u32_e32 v64, 0, v193
	s_nop 0
	v_addc_co_u32_e32 v49, vcc, 0, v45, vcc
	global_load_dwordx4 v[50:53], v[48:49], off offset:-4096
	s_waitcnt vmcnt(3)
	v_add_u32_e32 v65, 0, v194
	s_mov_b32 s52, 0
	s_mov_b32 s53, s52
	s_mov_b32 s9, s3
	s_mov_b32 s54, s52
	s_mov_b32 s55, s52
	s_mov_b32 s56, s52
	s_mov_b32 s57, s52
	s_mov_b32 s58, s52
	s_mov_b32 s59, s52
	s_mov_b32 s60, s52
	s_mov_b32 s61, s52
	s_mov_b32 s62, s52
	s_mov_b32 s63, s52
	s_mov_b32 s64, s52
	s_mov_b32 s65, s52
	s_mov_b32 s66, s52
	s_mov_b32 s67, s52
	s_lshl_b64 s[30:31], s[8:9], 8
	s_add_u32 s30, s30, s72
	s_addc_u32 s31, s31, s73
	s_mov_b32 s28, 1
	s_mov_b32 s2, 2
	v_lshl_add_u64 v[184:185], v[166:167], 0, s[74:75]
	v_lshl_add_u64 v[186:187], s[30:31], 0, v[168:169]
	v_mov_b32_e32 v171, 0
	v_mov_b32_e32 v175, 1.0
	s_mov_b32 s9, 2
	s_waitcnt vmcnt(7)
	ds_write_b128 v196, v[24:27]
	s_waitcnt vmcnt(6)
	ds_write_b128 v64, v[28:31] offset:24576
	s_waitcnt vmcnt(5)
	ds_write_b128 v65, v[32:35] offset:24576
	v_mov_b32_e32 v44, v16
	v_mov_b32_e32 v47, v16
	v_mov_b32_e32 v16, v21
	v_and_b32_e32 v61, 0xffff0000, v8
	v_and_b32_e32 v60, 0xffff0000, v12
	v_mov_b32_e32 v45, v20
	v_mov_b32_e32 v46, v20
	v_mov_b32_e32 v20, v17
	v_pk_mul_f32 v[16:17], v[16:17], v[60:61]
	s_waitcnt lgkmcnt(0)
	v_add_f32_e32 v67, v16, v17
	s_barrier
	s_waitcnt vmcnt(0)
	s_waitcnt vmcnt(2)
	ds_write_b128 v196, v[36:39] offset:8192
	s_waitcnt vmcnt(1)
	ds_write_b128 v64, v[40:43] offset:40960
	v_add_u32_e32 v16, 0, v198
	ds_read_b128 v[24:27], v16 offset:24576
	v_mov_b32_e32 v54, v18
	v_mov_b32_e32 v55, v22
	v_mov_b32_e32 v56, v22
	v_mov_b32_e32 v57, v18
	v_lshlrev_b32_e32 v59, 16, v8
	v_lshlrev_b32_e32 v58, 16, v12
	v_lshlrev_b32_e32 v63, 16, v9
	v_lshlrev_b32_e32 v62, 16, v13
	v_and_b32_e32 v9, 0xffff0000, v9
	v_pk_mul_f32 v[44:45], v[44:45], v[58:59]
	v_pk_mul_f32 v[46:47], v[46:47], v[58:59]
	v_pk_mul_f32 v[54:55], v[54:55], v[62:63]
	v_pk_mul_f32 v[56:57], v[56:57], v[62:63]
	v_and_b32_e32 v8, 0xffff0000, v13
	v_mov_b32_e32 v22, v19
	v_mov_b32_e32 v18, v23
	v_add_u32_e32 v58, 0, v199
	v_sub_f32_e32 v68, v55, v54
	v_add_f32_e32 v69, v56, v57
	v_pk_mul_f32 v[12:13], v[22:23], v[8:9]
	v_pk_mul_f32 v[8:9], v[18:19], v[8:9]
	ds_read_b128 v[54:57], v58 offset:24576
	ds_read_b128 v[16:19], v16 offset:32768
	v_sub_f32_e32 v62, v45, v44
	v_add_f32_e32 v63, v46, v47
	s_waitcnt lgkmcnt(2)
	v_mfma_f32_32x32x16_bf16 v[32:47], v[24:27], v[116:119], 0
	v_sub_f32_e32 v64, v13, v12
	v_add_f32_e32 v70, v8, v9
	v_lshlrev_b32_e32 v9, 16, v10
	v_lshlrev_b32_e32 v8, 16, v14
	v_mov_b32_e32 v12, v0
	v_mov_b32_e32 v13, v4
	v_pk_mul_f32 v[12:13], v[12:13], v[8:9]
	v_pk_mul_f32 v[20:21], v[20:21], v[60:61]
	v_sub_f32_e32 v71, v13, v12
	v_mov_b32_e32 v12, v4
	v_mov_b32_e32 v13, v0
	ds_read_b128 v[58:61], v58 offset:32768
	v_sub_f32_e32 v66, v21, v20
	s_waitcnt lgkmcnt(1)
	v_mfma_f32_32x32x16_bf16 v[16:31], v[16:19], v[116:119], 0
	v_mul_f32_e64 v8, v12, v8
	v_mul_f32_e64 v9, v13, v9
	v_mov_b32_e32 v4, v1
	v_add_f32_e32 v72, v8, v9
	v_and_b32_e32 v9, 0xffff0000, v10
	v_add_u32_e32 v10, 0, v200
	v_and_b32_e32 v8, 0xffff0000, v14
	v_mov_b32_e32 v0, v5
	v_mfma_f32_32x32x16_bf16 v[32:47], v[54:57], v[112:115], v[32:47]
	ds_read_b128 v[54:57], v10 offset:24576
	v_mul_f32_e64 v12, v4, v8
	v_mul_f32_e64 v13, v5, v9
	v_mul_f32_e64 v0, v0, v8
	v_mul_f32_e64 v1, v1, v9
	v_sub_f32_e32 v12, v13, v12
	v_add_f32_e32 v13, v0, v1
	v_lshlrev_b32_e32 v1, 16, v11
	v_lshlrev_b32_e32 v0, 16, v15
	s_waitcnt lgkmcnt(1)
	v_mfma_f32_32x32x16_bf16 v[16:31], v[58:61], v[112:115], v[16:31]
	v_mov_b32_e32 v4, v2
	v_mov_b32_e32 v5, v6
	ds_read_b128 v[58:61], v10 offset:32768
	v_mul_f32_e64 v4, v4, v0
	v_mul_f32_e64 v5, v5, v1
	global_load_dwordx4 v[144:147], v[48:49], off
	v_sub_f32_e32 v14, v5, v4
	v_mov_b32_e32 v5, v2
	v_add_u32_e32 v2, 0, v201
	s_waitcnt lgkmcnt(1)
	v_mfma_f32_32x32x16_bf16 v[32:47], v[54:57], v[124:127], v[32:47]
	ds_read_b128 v[54:57], v2 offset:24576
	v_mov_b32_e32 v4, v6
	v_mul_f32_e64 v0, v4, v0
	v_mul_f32_e64 v1, v5, v1
	v_mov_b32_e32 v6, v3
	v_lshl_add_u64 v[48:49], s[76:77], 0, v[158:159]
	s_waitcnt vmcnt(1)
	ds_write_b128 v65, v[50:53] offset:40960
	v_lshl_add_u64 v[48:49], v[48:49], 0, v[150:151]
	s_waitcnt lgkmcnt(2)
	v_mfma_f32_32x32x16_bf16 v[16:31], v[58:61], v[124:127], v[16:31]
	v_add_f32_e32 v58, v0, v1
	v_and_b32_e32 v1, 0xffff0000, v11
	v_and_b32_e32 v0, 0xffff0000, v15
	ds_read_b128 v[8:11], v2 offset:32768
	v_mov_b32_e32 v2, v7
	v_pk_mul_f32 v[4:5], v[6:7], v[0:1]
	v_pk_mul_f32 v[0:1], v[2:3], v[0:1]
	v_add_u32_e32 v6, 0, v202
	v_sub_f32_e32 v4, v5, v4
	v_add_f32_e32 v5, v0, v1
	ds_read_b128 v[0:3], v6 offset:24576
	s_waitcnt lgkmcnt(3)
	v_mfma_f32_32x32x16_bf16 v[32:47], v[54:57], v[120:123], v[32:47]
	v_cvt_pk_bf16_f32 v132, v62, v66
	v_cvt_pk_bf16_f32 v133, v68, v64
	v_cvt_pk_bf16_f32 v134, v71, v12
	v_cvt_pk_bf16_f32 v135, v14, v4
	v_cvt_pk_bf16_f32 v131, v58, v5
	ds_read_b128 v[4:7], v6 offset:32768
	v_cvt_pk_bf16_f32 v128, v63, v67
	s_waitcnt lgkmcnt(2)
	v_mfma_f32_32x32x16_bf16 v[16:31], v[8:11], v[120:123], v[16:31]
	v_add_u32_e32 v8, 0, v203
	ds_read_b128 v[50:53], v8 offset:32768
	v_cvt_pk_bf16_f32 v129, v69, v70
	v_cvt_pk_bf16_f32 v130, v72, v13
	s_waitcnt lgkmcnt(2)
	v_mfma_f32_32x32x16_bf16 v[32:47], v[0:3], v[132:135], v[32:47]
	ds_read_b128 v[0:3], v8 offset:24576
	global_load_dwordx4 v[140:143], v[48:49], off
	global_load_dwordx4 v[136:139], v[48:49], off offset:128
	s_waitcnt lgkmcnt(2)
	v_mfma_f32_32x32x16_bf16 v[16:31], v[4:7], v[132:135], v[16:31]
	s_waitcnt lgkmcnt(0)
	v_mfma_f32_32x32x16_bf16 v[32:47], v[0:3], v[128:131], v[32:47]
	v_mov_b64_e32 v[0:1], s[52:53]
	v_mov_b64_e32 v[14:15], s[66:67]
	v_mov_b64_e32 v[2:3], s[54:55]
	v_mov_b64_e32 v[4:5], s[56:57]
	v_mov_b64_e32 v[6:7], s[58:59]
	v_mov_b64_e32 v[8:9], s[60:61]
	v_mov_b64_e32 v[10:11], s[62:63]
	v_mfma_f32_32x32x16_bf16 v[16:31], v[50:53], v[128:131], v[16:31]
	s_nop 3
	v_max_f32_e32 v50, v33, v33
	v_max_f32_e32 v51, v32, v32
	v_max_f32_e32 v50, v51, v50
	v_max3_f32 v50, v50, v34, v35
	v_max3_f32 v50, v50, v36, v37
	v_max3_f32 v50, v50, v38, v39
	v_max3_f32 v50, v50, v40, v41
	v_max3_f32 v50, v50, v42, v43
	v_max3_f32 v50, v50, v44, v45
	v_max3_f32 v50, v50, v46, v47
	v_max3_f32 v50, v50, v16, v17
	v_max3_f32 v50, v50, v18, v19
	v_max3_f32 v50, v50, v20, v21
	v_max3_f32 v50, v50, v22, v23
	v_max3_f32 v50, v50, v24, v25
	v_max3_f32 v50, v50, v26, v27
	v_max3_f32 v50, v50, v28, v29
	v_max3_f32 v50, v50, v30, v31
	v_mov_b32_e32 v51, v50
	s_nop 1
	v_permlane32_swap_b32_e32 v50, v51
	v_max_f32_e32 v48, v51, v51
	v_max_f32_e32 v49, v50, v50
	v_max_f32_e32 v48, v49, v48
	v_sub_f32_e32 v32, v32, v48
	v_exp_f32_e32 v215, v32
	v_sub_f32_e32 v32, v33, v48
	v_exp_f32_e32 v219, v32
	v_sub_f32_e32 v32, v34, v48
	v_exp_f32_e32 v216, v32
	v_sub_f32_e32 v32, v35, v48
	v_exp_f32_e32 v220, v32
	v_sub_f32_e32 v32, v36, v48
	v_exp_f32_e32 v217, v32
	v_sub_f32_e32 v32, v37, v48
	v_exp_f32_e32 v221, v32
	v_sub_f32_e32 v32, v38, v48
	v_exp_f32_e32 v218, v32
	v_sub_f32_e32 v32, v39, v48
	v_exp_f32_e32 v222, v32
	v_sub_f32_e32 v32, v40, v48
	v_exp_f32_e32 v188, v32
	v_sub_f32_e32 v32, v41, v48
	v_exp_f32_e32 v211, v32
	v_sub_f32_e32 v32, v42, v48
	v_exp_f32_e32 v189, v32
	v_sub_f32_e32 v32, v43, v48
	v_exp_f32_e32 v212, v32
	v_sub_f32_e32 v32, v44, v48
	v_exp_f32_e32 v190, v32
	v_sub_f32_e32 v32, v45, v48
	v_exp_f32_e32 v213, v32
	v_sub_f32_e32 v32, v46, v48
	v_exp_f32_e32 v191, v32
	v_sub_f32_e32 v32, v47, v48
	v_exp_f32_e32 v214, v32
	v_mov_b64_e32 v[12:13], s[64:65]
	v_sub_f32_e32 v79, v31, v48
	v_sub_f32_e32 v78, v30, v48
	v_sub_f32_e32 v77, v29, v48
	v_sub_f32_e32 v76, v28, v48
	v_sub_f32_e32 v75, v27, v48
	v_sub_f32_e32 v74, v26, v48
	v_sub_f32_e32 v73, v25, v48
	v_sub_f32_e32 v72, v24, v48
	v_sub_f32_e32 v71, v23, v48
	v_sub_f32_e32 v70, v22, v48
	v_sub_f32_e32 v69, v21, v48
	v_sub_f32_e32 v68, v20, v48
	v_sub_f32_e32 v67, v19, v48
	v_sub_f32_e32 v66, v18, v48
	v_sub_f32_e32 v65, v17, v48
	v_sub_f32_e32 v64, v16, v48
	v_sub_f32_e32 v48, 0, v48
	v_mov_b64_e32 v[30:31], v[14:15]
	v_mov_b64_e32 v[28:29], v[12:13]
	v_mov_b64_e32 v[26:27], v[10:11]
	v_mov_b64_e32 v[24:25], v[8:9]
	v_mov_b64_e32 v[22:23], v[6:7]
	v_mov_b64_e32 v[20:21], v[4:5]
	v_mov_b64_e32 v[18:19], v[2:3]
	v_mov_b64_e32 v[16:17], v[0:1]
	v_mov_b32_e32 v49, v48
	v_mov_b32_e32 v50, v48
	v_mov_b32_e32 v51, v48
	v_mov_b32_e32 v52, v48
	v_mov_b32_e32 v53, v48
	v_mov_b32_e32 v54, v48
	v_mov_b32_e32 v55, v48
	v_mov_b32_e32 v56, v48
	v_mov_b32_e32 v57, v48
	v_mov_b32_e32 v58, v48
	v_mov_b32_e32 v59, v48
	v_mov_b32_e32 v60, v48
	v_mov_b32_e32 v61, v48
	v_mov_b32_e32 v62, v48
	v_mov_b32_e32 v63, v48
